# adds hand-written weight-conversion phase (one transpose routine, 16-byte loads all in flight per item) and scan v2 (loads spread through the step, 16-byte output stores via LDS transpose)
# speedup vs baseline: 1.0720x; 1.0260x over previous
.LBB0_34:
	v_and_b32_e32 v1, 63, v206
	v_lshrrev_b32_e32 v15, 6, v206
	v_and_b32_e32 v2, 31, v1
	v_readfirstlane_b32 s7, v15
	v_lshrrev_b32_e32 v3, 5, v1
	v_and_b32_e32 v8, 7, v1
	v_lshrrev_b32_e32 v9, 3, v1
	s_lshl_b32 s8, s72, 3
	s_add_u32 s8, s8, s7
	s_mul_i32 s9, s7, 0x2100
	v_mul_u32_u24_e32 v10, 33, v9
	v_lshl_add_u32 v10, v8, 2, v10
	v_lshlrev_b32_e32 v10, 2, v10
	v_add_u32_e32 v10, s9, v10
	v_lshlrev_b32_e32 v2, 2, v8
	v_mul_u32_u24_e32 v11, 0x108, v8
	v_add_lshl_u32 v11, v11, v9, 2
	v_add_u32_e32 v11, s9, v11
	v_lshlrev_b32_e32 v14, 5, v8
	v_readlane_b32 s22, v248, 8
	v_readlane_b32 s23, v248, 9
	s_mul_i32 s21, s6, 0x2110000
	s_add_u32 s22, s22, s21
	s_addc_u32 s23, s23, 0
	v_readlane_b32 s24, v248, 6
	v_readlane_b32 s25, v248, 7
	s_lshl_b32 s21, s6, 12
	s_add_u32 s24, s24, s21
	s_addc_u32 s25, s25, 0
	v_readlane_b32 s26, v248, 28
	v_readlane_b32 s27, v248, 29
	s_lshl_b32 s21, s6, 21
	s_add_u32 s26, s26, s21
	s_addc_u32 s27, s27, 0
	v_readlane_b32 s28, v248, 30
	v_readlane_b32 s29, v248, 31
	s_lshl_b32 s21, s6, 21
	s_add_u32 s28, s28, s21
	s_addc_u32 s29, s29, 0
	v_readlane_b32 s30, v248, 32
	v_readlane_b32 s31, v248, 33
	s_lshl_b32 s21, s6, 22
	s_add_u32 s30, s30, s21
	s_addc_u32 s31, s31, 0
	v_readlane_b32 s34, v248, 34
	v_readlane_b32 s35, v248, 35
	s_lshl_b32 s21, s6, 22
	s_add_u32 s34, s34, s21
	s_addc_u32 s35, s35, 0
	v_readlane_b32 s36, v248, 36
	v_readlane_b32 s37, v248, 37
	s_lshl_b32 s21, s6, 12
	s_add_u32 s36, s36, s21
	s_addc_u32 s37, s37, 0
	v_readlane_b32 s38, v248, 38
	v_readlane_b32 s39, v248, 39
	s_lshl_b32 s21, s6, 24
	s_add_u32 s38, s38, s21
	s_addc_u32 s39, s39, 0
	s_lshl_b32 s21, s6, 24
	s_add_u32 s40, s64, s21
	s_addc_u32 s41, s65, 0
	s_lshl_b32 s21, s72, 9
	v_add_u32_e32 v15, s21, v206
	v_cmp_gt_u32_e32 vcc, 0x7000, v15
	s_and_saveexec_b64 s[0:1], vcc
	v_lshlrev_b32_e32 v15, 4, v15
	v_mov_b32_e32 v88, 0
	v_mov_b32_e32 v89, 0
	v_mov_b32_e32 v90, 0
	v_mov_b32_e32 v91, 0
	s_add_u32 s2, s70, 0xd90000
	s_addc_u32 s3, s71, 0
	global_store_dwordx4 v15, v[88:91], s[2:3]
	s_mov_b64 exec, s[0:1]
	s_branch .Lconv_test
.Lconv_item:
	s_mov_b32 s20, s8
	s_cmp_lt_u32 s20, 2704
	s_cbranch_scc0 .Lconv_seg1
	s_mov_b64 s[10:11], s[22:23]
	s_mov_b32 s12, 0x8440
	s_movk_i32 s13, 0x400
	s_movk_i32 s15, 0x1510
	s_mov_b64 s[16:17], s[24:25]
	s_add_u32 s18, s70, 0x300000
	s_addc_u32 s19, s71, 0
	s_mul_hi_u32 s2, s20, 0x183c978
	s_mul_i32 s3, s2, 169
	s_sub_u32 s3, s20, s3
	s_branch .Lconv_go
.Lconv_seg1:
	s_sub_u32 s20, s20, 2704
	s_cmp_lt_u32 s20, 1536
	s_cbranch_scc0 .Lconv_seg2
	s_add_u32 s10, s22, 0x5440
	s_addc_u32 s11, s23, 0
	s_mov_b32 s12, 0x8440
	s_movk_i32 s13, 0x400
	s_movk_i32 s15, 0xc00
	s_mov_b64 s[16:17], s[24:25]
	s_add_u32 s18, s70, 0xe00000
	s_addc_u32 s19, s71, 0
	s_mul_hi_u32 s2, s20, 0x2aaaaab
	s_mul_i32 s3, s2, 96
	s_sub_u32 s3, s20, s3
	s_branch .Lconv_go
.Lconv_seg2:
	s_sub_u32 s20, s20, 1536
	s_cmp_lt_u32 s20, 256
	s_cbranch_scc0 .Lconv_seg3
	s_mov_b64 s[10:11], s[26:27]
	s_mov_b32 s12, 0x1000
	s_movk_i32 s13, 0x200
	s_movk_i32 s15, 0x400
	s_mov_b64 s[16:17], 0
	s_add_u32 s18, s70, 0x1400000
	s_addc_u32 s19, s71, 0
	s_lshr_b32 s2, s20, 5
	s_and_b32 s3, s20, 31
	s_branch .Lconv_go
.Lconv_seg3:
	s_sub_u32 s20, s20, 256
	s_cmp_lt_u32 s20, 256
	s_cbranch_scc0 .Lconv_seg4
	s_mov_b64 s[10:11], s[28:29]
	s_mov_b32 s12, 0x1000
	s_movk_i32 s13, 0x200
	s_movk_i32 s15, 0x400
	s_mov_b64 s[16:17], 0
	s_add_u32 s18, s70, 0x1500000
	s_addc_u32 s19, s71, 0
	s_lshr_b32 s2, s20, 5
	s_and_b32 s3, s20, 31
	s_branch .Lconv_go
.Lconv_seg4:
	s_sub_u32 s20, s20, 256
	s_cmp_lt_u32 s20, 512
	s_cbranch_scc0 .Lconv_seg5
	s_mov_b64 s[10:11], s[30:31]
	s_mov_b32 s12, 0x1000
	s_movk_i32 s13, 0x400
	s_movk_i32 s15, 0x400
	s_mov_b64 s[16:17], 0
	s_add_u32 s18, s70, 0x1600000
	s_addc_u32 s19, s71, 0
	s_lshr_b32 s2, s20, 5
	s_and_b32 s3, s20, 31
	s_branch .Lconv_go
.Lconv_seg5:
	s_sub_u32 s20, s20, 512
	s_cmp_lt_u32 s20, 512
	s_cbranch_scc0 .Lconv_seg6
	s_mov_b64 s[10:11], s[34:35]
	s_mov_b32 s12, 0x1000
	s_movk_i32 s13, 0x400
	s_movk_i32 s15, 0x400
	s_mov_b64 s[16:17], 0
	s_add_u32 s18, s70, 0x1800000
	s_addc_u32 s19, s71, 0
	s_lshr_b32 s2, s20, 5
	s_and_b32 s3, s20, 31
	s_branch .Lconv_go
.Lconv_seg6:
	s_sub_u32 s20, s20, 512
	s_cmp_lt_u32 s20, 2048
	s_cbranch_scc0 .Lconv_seg7
	s_mov_b64 s[10:11], s[38:39]
	s_mov_b32 s12, 0x4000
	s_movk_i32 s13, 0x400
	s_movk_i32 s15, 0x1000
	s_mov_b64 s[16:17], s[36:37]
	s_add_u32 s18, s70, 0x1a00000
	s_addc_u32 s19, s71, 0
	s_lshr_b32 s2, s20, 7
	s_and_b32 s3, s20, 127
	s_branch .Lconv_go
.Lconv_seg7:
	s_sub_u32 s20, s20, 2048
	s_mov_b64 s[10:11], s[40:41]
	s_mov_b32 s12, 0x1000
	s_movk_i32 s13, 0x1000
	s_movk_i32 s15, 0x400
	s_mov_b64 s[16:17], 0
	s_add_u32 s18, s70, 0x2200000
	s_addc_u32 s19, s71, 0
	s_lshr_b32 s2, s20, 5
	s_and_b32 s3, s20, 31
	s_branch .Lconv_go
.Lconv_go:
	s_lshl_b32 s2, s2, 6
	s_lshl_b32 s3, s3, 5
	s_mul_i32 s21, s2, s12
	s_lshl_b32 s33, s3, 2
	s_add_u32 s21, s21, s33
	s_add_u32 s44, s10, s21
	s_addc_u32 s45, s11, 0
	s_lshl_b32 s42, s12, 3
	v_mul_lo_u32 v12, v9, s12
	v_lshl_add_u32 v12, v8, 4, v12
	s_sub_u32 s43, s15, s3
	v_cmp_gt_u32_e32 vcc, s43, v2
	v_mov_b32_e32 v16, 0
	v_mov_b32_e32 v17, 0
	v_mov_b32_e32 v18, 0
	v_mov_b32_e32 v19, 0
	v_mov_b32_e32 v20, 0
	v_mov_b32_e32 v21, 0
	v_mov_b32_e32 v22, 0
	v_mov_b32_e32 v23, 0
	v_mov_b32_e32 v24, 0
	v_mov_b32_e32 v25, 0
	v_mov_b32_e32 v26, 0
	v_mov_b32_e32 v27, 0
	v_mov_b32_e32 v28, 0
	v_mov_b32_e32 v29, 0
	v_mov_b32_e32 v30, 0
	v_mov_b32_e32 v31, 0
	v_mov_b32_e32 v32, 0
	v_mov_b32_e32 v33, 0
	v_mov_b32_e32 v34, 0
	v_mov_b32_e32 v35, 0
	v_mov_b32_e32 v36, 0
	v_mov_b32_e32 v37, 0
	v_mov_b32_e32 v38, 0
	v_mov_b32_e32 v39, 0
	v_mov_b32_e32 v40, 0
	v_mov_b32_e32 v41, 0
	v_mov_b32_e32 v42, 0
	v_mov_b32_e32 v43, 0
	v_mov_b32_e32 v44, 0
	v_mov_b32_e32 v45, 0
	v_mov_b32_e32 v46, 0
	v_mov_b32_e32 v47, 0
	s_and_saveexec_b64 s[0:1], vcc
	global_load_dwordx4 v[16:19], v12, s[44:45]
	s_add_u32 s44, s44, s42
	s_addc_u32 s45, s45, 0
	global_load_dwordx4 v[20:23], v12, s[44:45]
	s_add_u32 s44, s44, s42
	s_addc_u32 s45, s45, 0
	global_load_dwordx4 v[24:27], v12, s[44:45]
	s_add_u32 s44, s44, s42
	s_addc_u32 s45, s45, 0
	global_load_dwordx4 v[28:31], v12, s[44:45]
	s_add_u32 s44, s44, s42
	s_addc_u32 s45, s45, 0
	global_load_dwordx4 v[32:35], v12, s[44:45]
	s_add_u32 s44, s44, s42
	s_addc_u32 s45, s45, 0
	global_load_dwordx4 v[36:39], v12, s[44:45]
	s_add_u32 s44, s44, s42
	s_addc_u32 s45, s45, 0
	global_load_dwordx4 v[40:43], v12, s[44:45]
	s_add_u32 s44, s44, s42
	s_addc_u32 s45, s45, 0
	global_load_dwordx4 v[44:47], v12, s[44:45]
	s_mov_b64 exec, s[0:1]
	s_cmp_eq_u64 s[16:17], 0
	s_cbranch_scc1 .Lconv_nogain
	s_lshl_b32 s21, s2, 2
	s_add_u32 s44, s16, s21
	s_addc_u32 s45, s17, 0
	global_load_dwordx4 v[80:83], v14, s[44:45]
	global_load_dwordx4 v[84:87], v14, s[44:45] offset:16
	s_branch .Lconv_gdone
.Lconv_nogain:
	v_mov_b32_e32 v80, 1.0
	v_mov_b32_e32 v81, 1.0
	v_mov_b32_e32 v82, 1.0
	v_mov_b32_e32 v83, 1.0
	v_mov_b32_e32 v84, 1.0
	v_mov_b32_e32 v85, 1.0
	v_mov_b32_e32 v86, 1.0
	v_mov_b32_e32 v87, 1.0
.Lconv_gdone:
	s_mul_i32 s21, s3, s13
	s_add_u32 s21, s21, s2
	s_lshl_b32 s21, s21, 1
	s_add_u32 s44, s18, s21
	s_addc_u32 s45, s19, 0
	s_lshl_b32 s42, s13, 4
	v_mul_lo_u32 v13, v9, s13
	v_lshlrev_b32_e32 v13, 1, v13
	v_lshl_add_u32 v13, v8, 4, v13
	s_waitcnt vmcnt(0)
	ds_write_b32 v10, v16
	ds_write_b32 v10, v17 offset:4
	ds_write_b32 v10, v18 offset:8
	ds_write_b32 v10, v19 offset:12
	ds_write_b32 v10, v20 offset:1056
	ds_write_b32 v10, v21 offset:1060
	ds_write_b32 v10, v22 offset:1064
	ds_write_b32 v10, v23 offset:1068
	ds_write_b32 v10, v24 offset:2112
	ds_write_b32 v10, v25 offset:2116
	ds_write_b32 v10, v26 offset:2120
	ds_write_b32 v10, v27 offset:2124
	ds_write_b32 v10, v28 offset:3168
	ds_write_b32 v10, v29 offset:3172
	ds_write_b32 v10, v30 offset:3176
	ds_write_b32 v10, v31 offset:3180
	ds_write_b32 v10, v32 offset:4224
	ds_write_b32 v10, v33 offset:4228
	ds_write_b32 v10, v34 offset:4232
	ds_write_b32 v10, v35 offset:4236
	ds_write_b32 v10, v36 offset:5280
	ds_write_b32 v10, v37 offset:5284
	ds_write_b32 v10, v38 offset:5288
	ds_write_b32 v10, v39 offset:5292
	ds_write_b32 v10, v40 offset:6336
	ds_write_b32 v10, v41 offset:6340
	ds_write_b32 v10, v42 offset:6344
	ds_write_b32 v10, v43 offset:6348
	ds_write_b32 v10, v44 offset:7392
	ds_write_b32 v10, v45 offset:7396
	ds_write_b32 v10, v46 offset:7400
	ds_write_b32 v10, v47 offset:7404
	s_waitcnt lgkmcnt(0)
	ds_read_b32 v48, v11
	ds_read_b32 v49, v11 offset:132
	ds_read_b32 v50, v11 offset:264
	ds_read_b32 v51, v11 offset:396
	ds_read_b32 v52, v11 offset:528
	ds_read_b32 v53, v11 offset:660
	ds_read_b32 v54, v11 offset:792
	ds_read_b32 v55, v11 offset:924
	s_waitcnt lgkmcnt(0)
	ds_read_b32 v56, v11 offset:32
	ds_read_b32 v57, v11 offset:164
	ds_read_b32 v58, v11 offset:296
	ds_read_b32 v59, v11 offset:428
	ds_read_b32 v60, v11 offset:560
	ds_read_b32 v61, v11 offset:692
	ds_read_b32 v62, v11 offset:824
	ds_read_b32 v63, v11 offset:956
	v_mul_f32_e32 v48, v48, v80
	v_mul_f32_e32 v49, v49, v81
	v_mul_f32_e32 v50, v50, v82
	v_mul_f32_e32 v51, v51, v83
	v_mul_f32_e32 v52, v52, v84
	v_mul_f32_e32 v53, v53, v85
	v_mul_f32_e32 v54, v54, v86
	v_mul_f32_e32 v55, v55, v87
	v_cvt_pk_bf16_f32 v88, v48, v49
	v_cvt_pk_bf16_f32 v89, v50, v51
	v_cvt_pk_bf16_f32 v90, v52, v53
	v_cvt_pk_bf16_f32 v91, v54, v55
	global_store_dwordx4 v13, v[88:91], s[44:45]
	s_add_u32 s44, s44, s42
	s_addc_u32 s45, s45, 0
	s_waitcnt lgkmcnt(0)
	ds_read_b32 v64, v11 offset:64
	ds_read_b32 v65, v11 offset:196
	ds_read_b32 v66, v11 offset:328
	ds_read_b32 v67, v11 offset:460
	ds_read_b32 v68, v11 offset:592
	ds_read_b32 v69, v11 offset:724
	ds_read_b32 v70, v11 offset:856
	ds_read_b32 v71, v11 offset:988
	v_mul_f32_e32 v56, v56, v80
	v_mul_f32_e32 v57, v57, v81
	v_mul_f32_e32 v58, v58, v82
	v_mul_f32_e32 v59, v59, v83
	v_mul_f32_e32 v60, v60, v84
	v_mul_f32_e32 v61, v61, v85
	v_mul_f32_e32 v62, v62, v86
	v_mul_f32_e32 v63, v63, v87
	v_cvt_pk_bf16_f32 v92, v56, v57
	v_cvt_pk_bf16_f32 v93, v58, v59
	v_cvt_pk_bf16_f32 v94, v60, v61
	v_cvt_pk_bf16_f32 v95, v62, v63
	global_store_dwordx4 v13, v[92:95], s[44:45]
	s_add_u32 s44, s44, s42
	s_addc_u32 s45, s45, 0
	s_waitcnt lgkmcnt(0)
	ds_read_b32 v72, v11 offset:96
	ds_read_b32 v73, v11 offset:228
	ds_read_b32 v74, v11 offset:360
	ds_read_b32 v75, v11 offset:492
	ds_read_b32 v76, v11 offset:624
	ds_read_b32 v77, v11 offset:756
	ds_read_b32 v78, v11 offset:888
	ds_read_b32 v79, v11 offset:1020
	v_mul_f32_e32 v64, v64, v80
	v_mul_f32_e32 v65, v65, v81
	v_mul_f32_e32 v66, v66, v82
	v_mul_f32_e32 v67, v67, v83
	v_mul_f32_e32 v68, v68, v84
	v_mul_f32_e32 v69, v69, v85
	v_mul_f32_e32 v70, v70, v86
	v_mul_f32_e32 v71, v71, v87
	v_cvt_pk_bf16_f32 v96, v64, v65
	v_cvt_pk_bf16_f32 v97, v66, v67
	v_cvt_pk_bf16_f32 v98, v68, v69
	v_cvt_pk_bf16_f32 v99, v70, v71
	global_store_dwordx4 v13, v[96:99], s[44:45]
	s_add_u32 s44, s44, s42
	s_addc_u32 s45, s45, 0
	s_waitcnt lgkmcnt(0)
	v_mul_f32_e32 v72, v72, v80
	v_mul_f32_e32 v73, v73, v81
	v_mul_f32_e32 v74, v74, v82
	v_mul_f32_e32 v75, v75, v83
	v_mul_f32_e32 v76, v76, v84
	v_mul_f32_e32 v77, v77, v85
	v_mul_f32_e32 v78, v78, v86
	v_mul_f32_e32 v79, v79, v87
	v_cvt_pk_bf16_f32 v100, v72, v73
	v_cvt_pk_bf16_f32 v101, v74, v75
	v_cvt_pk_bf16_f32 v102, v76, v77
	v_cvt_pk_bf16_f32 v103, v78, v79
	global_store_dwordx4 v13, v[100:103], s[44:45]
	s_lshl_b32 s21, s74, 3
	s_add_u32 s8, s8, s21
.Lconv_test:
	s_cmpk_lt_u32 s8, 0x2690
	s_cbranch_scc1 .Lconv_item
	s_mov_b64 s[0:1], exec

.LBB0_652:
	s_andn2_b64 vcc, exec, s[0:1]
	s_cbranch_vccnz .LBB0_704
	v_and_b32_e32 v14, 63, v206
	v_lshrrev_b32_e32 v15, 6, v206
	v_and_b32_e32 v64, 15, v14
	v_readfirstlane_b32 s11, v15
	v_lshrrev_b32_e32 v65, 4, v14
	v_lshlrev_b32_e32 v66, 2, v206
	ds_write_b32 v66, v0
	ds_write_b32 v66, v0 offset:2048
	ds_write_b32 v66, v0 offset:4096
	ds_write_b32 v66, v0 offset:6144
	ds_write_b32 v66, v0 offset:8192
	s_and_b32 s12, s11, 3
	s_and_b32 s13, s72, 7
	s_lshr_b32 s14, s72, 5
	s_bfe_u32 s15, s72, 0x20003
	s_lshl_b32 s16, s14, 3
	s_add_u32 s16, s16, s13
	s_lshl_b32 s17, s16, 21
	s_mov_b32 s18, 0x13800000
	s_cmp_lt_u32 s11, 4
	s_cselect_b32 s18, 0x11800000, s18
	s_add_u32 s18, s18, s17
	s_lshl_b32 s19, s12, 12
	s_add_u32 s18, s18, s19
	s_add_u32 s0, s70, s18
	s_addc_u32 s1, s71, 0
	s_lshl_b32 s19, s11, 11
	s_add_u32 s18, s17, s19
	s_add_u32 s18, s18, 0x15800000
	s_add_u32 s4, s70, s18
	s_addc_u32 s5, s71, 0
	s_lshl_b32 s18, s16, 9
	s_add_u32 s18, s18, 0x11500000
	s_add_u32 s6, s70, s18
	s_addc_u32 s7, s71, 0
	s_lshl_b32 s18, s15, 12
	s_lshl_b32 s19, s12, 9
	s_add_u32 s18, s18, s19
	s_add_u32 s18, s18, s17
	s_add_u32 s18, s18, 0x17800000
	s_lshl_b32 s19, s16, 20
	s_lshl_b32 s20, s12, 11
	s_add_u32 s19, s19, s20
	s_add_u32 s19, s19, 0x19800000
	s_cmp_lt_u32 s11, 4
	s_cselect_b32 s18, s18, s19
	s_add_u32 s2, s70, s18
	s_addc_u32 s3, s71, 0
	s_lshl_b32 s18, s14, 24
	s_lshl_b32 s19, s12, 15
	s_add_u32 s18, s18, s19
	s_lshl_b32 s19, s13, 8
	s_add_u32 s18, s18, s19
	s_lshl_b32 s19, s15, 6
	s_add_u32 s18, s18, s19
	s_add_u32 s18, s18, 0xb400000
	s_add_u32 s8, s70, s18
	s_addc_u32 s9, s71, 0
	v_lshlrev_b32_e32 v1, 4, v14
	v_mov_b32_e32 v3, 0
	v_mul_u32_u24_e32 v8, 0x110, v64
	v_mul_u32_u24_e32 v9, 0x90, v64
	v_lshl_add_u32 v11, v65, 3, v8
	v_lshl_add_u32 v10, v65, 3, v9
	v_lshl_add_u32 v8, v65, 4, v8
	v_lshl_add_u32 v9, v65, 4, v9
	s_lshl_b32 s18, s11, 5
	v_add_u32_e32 v11, s18, v11
	s_lshl_b32 s18, s12, 5
	v_add_u32_e32 v10, s18, v10
	s_mul_i32 s18, s12, 0x500
	s_add_u32 s18, s18, 0x5800
	v_mul_u32_u24_e32 v13, 0x140, v65
	v_lshl_add_u32 v13, v64, 1, v13
	v_add_u32_e32 v13, s18, v13
	v_lshrrev_b32_e32 v67, 2, v14
	v_and_b32_e32 v68, 3, v14
	v_mul_u32_u24_e32 v172, 0x50, v67
	v_lshl_add_u32 v172, v68, 4, v172
	v_add_u32_e32 v172, s18, v172
	v_lshlrev_b32_e32 v12, 11, v67
	v_lshl_add_u32 v12, v68, 4, v12
	v_mov_b32_e32 v16, 0
	v_mov_b32_e32 v17, 0
	v_mov_b32_e32 v18, 0
	v_mov_b32_e32 v19, 0
	v_mov_b32_e32 v20, 0
	v_mov_b32_e32 v21, 0
	v_mov_b32_e32 v22, 0
	v_mov_b32_e32 v23, 0
	s_cmp_lt_u32 s11, 4
	s_waitcnt lgkmcnt(0)
	s_barrier
	s_cbranch_scc0 .Lscan_O_path
	v_lshlrev_b32_e32 v2, 3, v14
	global_load_dwordx4 v[72:75], v1, s[0:1]
	global_load_dwordx4 v[76:79], v1, s[0:1] offset:1024
	global_load_dwordx4 v[80:83], v1, s[0:1] offset:2048
	global_load_dwordx4 v[84:87], v1, s[0:1] offset:3072
	global_load_dwordx2 v[88:89], v2, s[2:3]
	global_load_dwordx2 v[90:91], v2, s[2:3] offset:2048
	global_load_dwordx4 v[96:99], v1, s[4:5]
	global_load_dwordx4 v[100:103], v1, s[4:5] offset:1024
	global_load_dword v184, v3, s[6:7]
	v_add_u32_e32 v1, 0x4000, v1
	v_add_u32_e32 v2, 0x4000, v2
	v_add_u32_e32 v3, 4, v3
	global_load_dwordx4 v[104:107], v1, s[0:1]
	global_load_dwordx4 v[108:111], v1, s[0:1] offset:1024
	global_load_dwordx4 v[112:115], v1, s[0:1] offset:2048
	global_load_dwordx4 v[116:119], v1, s[0:1] offset:3072
	global_load_dwordx2 v[120:121], v2, s[2:3]
	global_load_dwordx2 v[122:123], v2, s[2:3] offset:2048
	global_load_dwordx4 v[128:131], v1, s[4:5]
	global_load_dwordx4 v[132:135], v1, s[4:5] offset:1024
	global_load_dword v185, v3, s[6:7]
	v_add_u32_e32 v1, 0x4000, v1
	v_add_u32_e32 v2, 0x4000, v2
	v_add_u32_e32 v3, 4, v3
	global_load_dwordx4 v[136:139], v1, s[0:1]
	global_load_dwordx4 v[140:143], v1, s[0:1] offset:1024
	global_load_dwordx4 v[144:147], v1, s[0:1] offset:2048
	global_load_dwordx4 v[148:151], v1, s[0:1] offset:3072
	global_load_dwordx2 v[188:189], v2, s[2:3]
	global_load_dwordx2 v[190:191], v2, s[2:3] offset:2048
	global_load_dwordx4 v[196:199], v1, s[4:5]
	global_load_dwordx4 v[200:203], v1, s[4:5] offset:1024
	global_load_dword v186, v3, s[6:7]
	v_add_u32_e32 v1, 0x4000, v1
	v_add_u32_e32 v2, 0x4000, v2
	v_add_u32_e32 v3, 4, v3
	s_waitcnt vmcnt(0)
	s_movk_i32 s10, 32
.Lscan_V_loop:
	s_waitcnt vmcnt(23)
	ds_read_b128 v[32:35], v8 offset:0
	ds_read_b128 v[36:39], v8 offset:4352
	ds_read_b128 v[40:43], v8 offset:64
	ds_read_b128 v[44:47], v8 offset:4416
	ds_read_b128 v[48:51], v8 offset:128
	ds_read_b128 v[52:55], v8 offset:4480
	ds_read_b128 v[56:59], v8 offset:192
	ds_read_b128 v[60:63], v8 offset:4544
	global_load_dwordx4 v[216:219], v1, s[0:1]
	global_load_dwordx4 v[220:223], v1, s[0:1] offset:1024
	s_waitcnt vmcnt(20)
	v_mul_f32_e32 v16, v184, v16
	v_mul_f32_e32 v17, v184, v17
	v_mul_f32_e32 v18, v184, v18
	v_mul_f32_e32 v19, v184, v19
	global_load_dwordx4 v[224:227], v1, s[0:1] offset:2048
	v_mul_f32_e32 v20, v184, v20
	v_mul_f32_e32 v21, v184, v21
	v_mul_f32_e32 v22, v184, v22
	v_mul_f32_e32 v23, v184, v23
	v_lshlrev_b32_e32 v64, 16, v88
	v_and_b32_e32 v65, 0xffff0000, v88
	v_lshlrev_b32_e32 v66, 16, v89
	v_and_b32_e32 v67, 0xffff0000, v89
	v_lshlrev_b32_e32 v68, 16, v90
	v_and_b32_e32 v69, 0xffff0000, v90
	v_lshlrev_b32_e32 v70, 16, v91
	v_and_b32_e32 v71, 0xffff0000, v91
	global_load_dwordx4 v[228:231], v1, s[0:1] offset:3072
	s_waitcnt lgkmcnt(6)
	v_mfma_f32_16x16x32_bf16 v[24:27], v[72:75], v[32:35], 0
	v_mfma_f32_16x16x32_bf16 v[28:31], v[72:75], v[36:39], 0
	global_load_dwordx2 v[232:233], v2, s[2:3]
	s_waitcnt lgkmcnt(4)
	v_mfma_f32_16x16x32_bf16 v[24:27], v[76:79], v[40:43], v[24:27]
	v_mfma_f32_16x16x32_bf16 v[28:31], v[76:79], v[44:47], v[28:31]
	global_load_dwordx2 v[234:235], v2, s[2:3] offset:2048
	s_waitcnt lgkmcnt(2)
	v_mfma_f32_16x16x32_bf16 v[24:27], v[80:83], v[48:51], v[24:27]
	v_mfma_f32_16x16x32_bf16 v[28:31], v[80:83], v[52:55], v[28:31]
	global_load_dwordx4 v[240:243], v1, s[4:5]
	s_waitcnt lgkmcnt(0)
	v_mfma_f32_16x16x32_bf16 v[24:27], v[84:87], v[56:59], v[24:27]
	v_mfma_f32_16x16x32_bf16 v[28:31], v[84:87], v[60:63], v[28:31]
	global_load_dwordx4 v[244:247], v1, s[4:5] offset:1024
	global_load_dword v187, v3, s[6:7]
	v_add_u32_e32 v1, 0x4000, v1
	v_add_u32_e32 v2, 0x4000, v2
	v_add_u32_e32 v3, 4, v3
	s_nop 2
	v_sub_f32_e32 v64, v64, v24
	v_sub_f32_e32 v65, v65, v25
	v_sub_f32_e32 v66, v66, v26
	v_sub_f32_e32 v67, v67, v27
	v_sub_f32_e32 v68, v68, v28
	v_sub_f32_e32 v69, v69, v29
	v_sub_f32_e32 v70, v70, v30
	v_sub_f32_e32 v71, v71, v31
	v_cvt_pk_bf16_f32 v64, v64, v65
	v_cvt_pk_bf16_f32 v65, v66, v67
	v_cvt_pk_bf16_f32 v68, v68, v69
	v_cvt_pk_bf16_f32 v69, v70, v71
	ds_write_b64 v10, v[64:65] offset:17408
	ds_write_b64 v10, v[68:69] offset:19712
	s_waitcnt lgkmcnt(0)
	s_barrier
	ds_read_b128 v[32:35], v9 offset:17408
	ds_read_b128 v[36:39], v9 offset:19712
	ds_read_b128 v[40:43], v9 offset:17472
	ds_read_b128 v[44:47], v9 offset:19776
	s_waitcnt lgkmcnt(2)
	v_mfma_f32_16x16x32_bf16 v[16:19], v[96:99], v[32:35], v[16:19]
	v_mfma_f32_16x16x32_bf16 v[20:23], v[96:99], v[36:39], v[20:23]
	s_waitcnt lgkmcnt(0)
	v_mfma_f32_16x16x32_bf16 v[16:19], v[100:103], v[40:43], v[16:19]
	v_mfma_f32_16x16x32_bf16 v[20:23], v[100:103], v[44:47], v[20:23]
	s_nop 7
	v_cvt_pk_bf16_f32 v64, v16, v17
	v_cvt_pk_bf16_f32 v65, v18, v19
	v_cvt_pk_bf16_f32 v66, v20, v21
	v_cvt_pk_bf16_f32 v67, v22, v23
	ds_write_b64 v11, v[64:65] offset:8704
	ds_write_b64 v11, v[66:67] offset:13056
	s_waitcnt lgkmcnt(0)
	s_barrier
	s_waitcnt vmcnt(23)
	ds_read_b128 v[32:35], v8 offset:8704
	ds_read_b128 v[36:39], v8 offset:13056
	ds_read_b128 v[40:43], v8 offset:8768
	ds_read_b128 v[44:47], v8 offset:13120
	ds_read_b128 v[48:51], v8 offset:8832
	ds_read_b128 v[52:55], v8 offset:13184
	ds_read_b128 v[56:59], v8 offset:8896
	ds_read_b128 v[60:63], v8 offset:13248
	global_load_dwordx4 v[72:75], v1, s[0:1]
	global_load_dwordx4 v[76:79], v1, s[0:1] offset:1024
	s_waitcnt vmcnt(20)
	v_mul_f32_e32 v16, v185, v16
	v_mul_f32_e32 v17, v185, v17
	v_mul_f32_e32 v18, v185, v18
	v_mul_f32_e32 v19, v185, v19
	global_load_dwordx4 v[80:83], v1, s[0:1] offset:2048
	v_mul_f32_e32 v20, v185, v20
	v_mul_f32_e32 v21, v185, v21
	v_mul_f32_e32 v22, v185, v22
	v_mul_f32_e32 v23, v185, v23
	v_lshlrev_b32_e32 v64, 16, v120
	v_and_b32_e32 v65, 0xffff0000, v120
	v_lshlrev_b32_e32 v66, 16, v121
	v_and_b32_e32 v67, 0xffff0000, v121
	v_lshlrev_b32_e32 v68, 16, v122
	v_and_b32_e32 v69, 0xffff0000, v122
	v_lshlrev_b32_e32 v70, 16, v123
	v_and_b32_e32 v71, 0xffff0000, v123
	global_load_dwordx4 v[84:87], v1, s[0:1] offset:3072
	s_waitcnt lgkmcnt(6)
	v_mfma_f32_16x16x32_bf16 v[24:27], v[104:107], v[32:35], 0
	v_mfma_f32_16x16x32_bf16 v[28:31], v[104:107], v[36:39], 0
	global_load_dwordx2 v[88:89], v2, s[2:3]
	s_waitcnt lgkmcnt(4)
	v_mfma_f32_16x16x32_bf16 v[24:27], v[108:111], v[40:43], v[24:27]
	v_mfma_f32_16x16x32_bf16 v[28:31], v[108:111], v[44:47], v[28:31]
	global_load_dwordx2 v[90:91], v2, s[2:3] offset:2048
	s_waitcnt lgkmcnt(2)
	v_mfma_f32_16x16x32_bf16 v[24:27], v[112:115], v[48:51], v[24:27]
	v_mfma_f32_16x16x32_bf16 v[28:31], v[112:115], v[52:55], v[28:31]
	global_load_dwordx4 v[96:99], v1, s[4:5]
	s_waitcnt lgkmcnt(0)
	v_mfma_f32_16x16x32_bf16 v[24:27], v[116:119], v[56:59], v[24:27]
	v_mfma_f32_16x16x32_bf16 v[28:31], v[116:119], v[60:63], v[28:31]
	global_load_dwordx4 v[100:103], v1, s[4:5] offset:1024
	global_load_dword v184, v3, s[6:7]
	v_add_u32_e32 v1, 0x4000, v1
	v_add_u32_e32 v2, 0x4000, v2
	v_add_u32_e32 v3, 4, v3
	s_nop 2
	v_sub_f32_e32 v64, v64, v24
	v_sub_f32_e32 v65, v65, v25
	v_sub_f32_e32 v66, v66, v26
	v_sub_f32_e32 v67, v67, v27
	v_sub_f32_e32 v68, v68, v28
	v_sub_f32_e32 v69, v69, v29
	v_sub_f32_e32 v70, v70, v30
	v_sub_f32_e32 v71, v71, v31
	v_cvt_pk_bf16_f32 v64, v64, v65
	v_cvt_pk_bf16_f32 v65, v66, v67
	v_cvt_pk_bf16_f32 v68, v68, v69
	v_cvt_pk_bf16_f32 v69, v70, v71
	ds_write_b64 v10, v[64:65] offset:17408
	ds_write_b64 v10, v[68:69] offset:19712
	s_waitcnt lgkmcnt(0)
	s_barrier
	ds_read_b128 v[32:35], v9 offset:17408
	ds_read_b128 v[36:39], v9 offset:19712
	ds_read_b128 v[40:43], v9 offset:17472
	ds_read_b128 v[44:47], v9 offset:19776
	s_waitcnt lgkmcnt(2)
	v_mfma_f32_16x16x32_bf16 v[16:19], v[128:131], v[32:35], v[16:19]
	v_mfma_f32_16x16x32_bf16 v[20:23], v[128:131], v[36:39], v[20:23]
	s_waitcnt lgkmcnt(0)
	v_mfma_f32_16x16x32_bf16 v[16:19], v[132:135], v[40:43], v[16:19]
	v_mfma_f32_16x16x32_bf16 v[20:23], v[132:135], v[44:47], v[20:23]
	s_nop 7
	v_cvt_pk_bf16_f32 v64, v16, v17
	v_cvt_pk_bf16_f32 v65, v18, v19
	v_cvt_pk_bf16_f32 v66, v20, v21
	v_cvt_pk_bf16_f32 v67, v22, v23
	ds_write_b64 v11, v[64:65] offset:0
	ds_write_b64 v11, v[66:67] offset:4352
	s_waitcnt lgkmcnt(0)
	s_barrier
	s_waitcnt vmcnt(23)
	ds_read_b128 v[32:35], v8 offset:0
	ds_read_b128 v[36:39], v8 offset:4352
	ds_read_b128 v[40:43], v8 offset:64
	ds_read_b128 v[44:47], v8 offset:4416
	ds_read_b128 v[48:51], v8 offset:128
	ds_read_b128 v[52:55], v8 offset:4480
	ds_read_b128 v[56:59], v8 offset:192
	ds_read_b128 v[60:63], v8 offset:4544
	global_load_dwordx4 v[104:107], v1, s[0:1]
	global_load_dwordx4 v[108:111], v1, s[0:1] offset:1024
	s_waitcnt vmcnt(20)
	v_mul_f32_e32 v16, v186, v16
	v_mul_f32_e32 v17, v186, v17
	v_mul_f32_e32 v18, v186, v18
	v_mul_f32_e32 v19, v186, v19
	global_load_dwordx4 v[112:115], v1, s[0:1] offset:2048
	v_mul_f32_e32 v20, v186, v20
	v_mul_f32_e32 v21, v186, v21
	v_mul_f32_e32 v22, v186, v22
	v_mul_f32_e32 v23, v186, v23
	v_lshlrev_b32_e32 v64, 16, v188
	v_and_b32_e32 v65, 0xffff0000, v188
	v_lshlrev_b32_e32 v66, 16, v189
	v_and_b32_e32 v67, 0xffff0000, v189
	v_lshlrev_b32_e32 v68, 16, v190
	v_and_b32_e32 v69, 0xffff0000, v190
	v_lshlrev_b32_e32 v70, 16, v191
	v_and_b32_e32 v71, 0xffff0000, v191
	global_load_dwordx4 v[116:119], v1, s[0:1] offset:3072
	s_waitcnt lgkmcnt(6)
	v_mfma_f32_16x16x32_bf16 v[24:27], v[136:139], v[32:35], 0
	v_mfma_f32_16x16x32_bf16 v[28:31], v[136:139], v[36:39], 0
	global_load_dwordx2 v[120:121], v2, s[2:3]
	s_waitcnt lgkmcnt(4)
	v_mfma_f32_16x16x32_bf16 v[24:27], v[140:143], v[40:43], v[24:27]
	v_mfma_f32_16x16x32_bf16 v[28:31], v[140:143], v[44:47], v[28:31]
	global_load_dwordx2 v[122:123], v2, s[2:3] offset:2048
	s_waitcnt lgkmcnt(2)
	v_mfma_f32_16x16x32_bf16 v[24:27], v[144:147], v[48:51], v[24:27]
	v_mfma_f32_16x16x32_bf16 v[28:31], v[144:147], v[52:55], v[28:31]
	global_load_dwordx4 v[128:131], v1, s[4:5]
	s_waitcnt lgkmcnt(0)
	v_mfma_f32_16x16x32_bf16 v[24:27], v[148:151], v[56:59], v[24:27]
	v_mfma_f32_16x16x32_bf16 v[28:31], v[148:151], v[60:63], v[28:31]
	global_load_dwordx4 v[132:135], v1, s[4:5] offset:1024
	global_load_dword v185, v3, s[6:7]
	v_add_u32_e32 v1, 0x4000, v1
	v_add_u32_e32 v2, 0x4000, v2
	v_add_u32_e32 v3, 4, v3
	s_nop 2
	v_sub_f32_e32 v64, v64, v24
	v_sub_f32_e32 v65, v65, v25
	v_sub_f32_e32 v66, v66, v26
	v_sub_f32_e32 v67, v67, v27
	v_sub_f32_e32 v68, v68, v28
	v_sub_f32_e32 v69, v69, v29
	v_sub_f32_e32 v70, v70, v30
	v_sub_f32_e32 v71, v71, v31
	v_cvt_pk_bf16_f32 v64, v64, v65
	v_cvt_pk_bf16_f32 v65, v66, v67
	v_cvt_pk_bf16_f32 v68, v68, v69
	v_cvt_pk_bf16_f32 v69, v70, v71
	ds_write_b64 v10, v[64:65] offset:17408
	ds_write_b64 v10, v[68:69] offset:19712
	s_waitcnt lgkmcnt(0)
	s_barrier
	ds_read_b128 v[32:35], v9 offset:17408
	ds_read_b128 v[36:39], v9 offset:19712
	ds_read_b128 v[40:43], v9 offset:17472
	ds_read_b128 v[44:47], v9 offset:19776
	s_waitcnt lgkmcnt(2)
	v_mfma_f32_16x16x32_bf16 v[16:19], v[196:199], v[32:35], v[16:19]
	v_mfma_f32_16x16x32_bf16 v[20:23], v[196:199], v[36:39], v[20:23]
	s_waitcnt lgkmcnt(0)
	v_mfma_f32_16x16x32_bf16 v[16:19], v[200:203], v[40:43], v[16:19]
	v_mfma_f32_16x16x32_bf16 v[20:23], v[200:203], v[44:47], v[20:23]
	s_nop 7
	v_cvt_pk_bf16_f32 v64, v16, v17
	v_cvt_pk_bf16_f32 v65, v18, v19
	v_cvt_pk_bf16_f32 v66, v20, v21
	v_cvt_pk_bf16_f32 v67, v22, v23
	ds_write_b64 v11, v[64:65] offset:8704
	ds_write_b64 v11, v[66:67] offset:13056
	s_waitcnt lgkmcnt(0)
	s_barrier
	s_waitcnt vmcnt(23)
	ds_read_b128 v[32:35], v8 offset:8704
	ds_read_b128 v[36:39], v8 offset:13056
	ds_read_b128 v[40:43], v8 offset:8768
	ds_read_b128 v[44:47], v8 offset:13120
	ds_read_b128 v[48:51], v8 offset:8832
	ds_read_b128 v[52:55], v8 offset:13184
	ds_read_b128 v[56:59], v8 offset:8896
	ds_read_b128 v[60:63], v8 offset:13248
	global_load_dwordx4 v[136:139], v1, s[0:1]
	global_load_dwordx4 v[140:143], v1, s[0:1] offset:1024
	s_waitcnt vmcnt(20)
	v_mul_f32_e32 v16, v187, v16
	v_mul_f32_e32 v17, v187, v17
	v_mul_f32_e32 v18, v187, v18
	v_mul_f32_e32 v19, v187, v19
	global_load_dwordx4 v[144:147], v1, s[0:1] offset:2048
	v_mul_f32_e32 v20, v187, v20
	v_mul_f32_e32 v21, v187, v21
	v_mul_f32_e32 v22, v187, v22
	v_mul_f32_e32 v23, v187, v23
	v_lshlrev_b32_e32 v64, 16, v232
	v_and_b32_e32 v65, 0xffff0000, v232
	v_lshlrev_b32_e32 v66, 16, v233
	v_and_b32_e32 v67, 0xffff0000, v233
	v_lshlrev_b32_e32 v68, 16, v234
	v_and_b32_e32 v69, 0xffff0000, v234
	v_lshlrev_b32_e32 v70, 16, v235
	v_and_b32_e32 v71, 0xffff0000, v235
	global_load_dwordx4 v[148:151], v1, s[0:1] offset:3072
	s_waitcnt lgkmcnt(6)
	v_mfma_f32_16x16x32_bf16 v[24:27], v[216:219], v[32:35], 0
	v_mfma_f32_16x16x32_bf16 v[28:31], v[216:219], v[36:39], 0
	global_load_dwordx2 v[188:189], v2, s[2:3]
	s_waitcnt lgkmcnt(4)
	v_mfma_f32_16x16x32_bf16 v[24:27], v[220:223], v[40:43], v[24:27]
	v_mfma_f32_16x16x32_bf16 v[28:31], v[220:223], v[44:47], v[28:31]
	global_load_dwordx2 v[190:191], v2, s[2:3] offset:2048
	s_waitcnt lgkmcnt(2)
	v_mfma_f32_16x16x32_bf16 v[24:27], v[224:227], v[48:51], v[24:27]
	v_mfma_f32_16x16x32_bf16 v[28:31], v[224:227], v[52:55], v[28:31]
	global_load_dwordx4 v[196:199], v1, s[4:5]
	s_waitcnt lgkmcnt(0)
	v_mfma_f32_16x16x32_bf16 v[24:27], v[228:231], v[56:59], v[24:27]
	v_mfma_f32_16x16x32_bf16 v[28:31], v[228:231], v[60:63], v[28:31]
	global_load_dwordx4 v[200:203], v1, s[4:5] offset:1024
	global_load_dword v186, v3, s[6:7]
	v_add_u32_e32 v1, 0x4000, v1
	v_add_u32_e32 v2, 0x4000, v2
	v_add_u32_e32 v3, 4, v3
	s_nop 2
	v_sub_f32_e32 v64, v64, v24
	v_sub_f32_e32 v65, v65, v25
	v_sub_f32_e32 v66, v66, v26
	v_sub_f32_e32 v67, v67, v27
	v_sub_f32_e32 v68, v68, v28
	v_sub_f32_e32 v69, v69, v29
	v_sub_f32_e32 v70, v70, v30
	v_sub_f32_e32 v71, v71, v31
	v_cvt_pk_bf16_f32 v64, v64, v65
	v_cvt_pk_bf16_f32 v65, v66, v67
	v_cvt_pk_bf16_f32 v68, v68, v69
	v_cvt_pk_bf16_f32 v69, v70, v71
	ds_write_b64 v10, v[64:65] offset:17408
	ds_write_b64 v10, v[68:69] offset:19712
	s_waitcnt lgkmcnt(0)
	s_barrier
	ds_read_b128 v[32:35], v9 offset:17408
	ds_read_b128 v[36:39], v9 offset:19712
	ds_read_b128 v[40:43], v9 offset:17472
	ds_read_b128 v[44:47], v9 offset:19776
	s_waitcnt lgkmcnt(2)
	v_mfma_f32_16x16x32_bf16 v[16:19], v[240:243], v[32:35], v[16:19]
	v_mfma_f32_16x16x32_bf16 v[20:23], v[240:243], v[36:39], v[20:23]
	s_waitcnt lgkmcnt(0)
	v_mfma_f32_16x16x32_bf16 v[16:19], v[244:247], v[40:43], v[16:19]
	v_mfma_f32_16x16x32_bf16 v[20:23], v[244:247], v[44:47], v[20:23]
	s_nop 7
	v_cvt_pk_bf16_f32 v64, v16, v17
	v_cvt_pk_bf16_f32 v65, v18, v19
	v_cvt_pk_bf16_f32 v66, v20, v21
	v_cvt_pk_bf16_f32 v67, v22, v23
	ds_write_b64 v11, v[64:65] offset:0
	ds_write_b64 v11, v[66:67] offset:4352
	s_waitcnt lgkmcnt(0)
	s_barrier
	s_sub_u32 s10, s10, 1
	s_cmp_lg_u32 s10, 0
	s_cbranch_scc1 .Lscan_V_loop
	s_branch .Lscan_done

.Lscan_O_loop:
	s_waitcnt vmcnt(26)
	ds_read_b128 v[32:35], v8 offset:0
	ds_read_b128 v[36:39], v8 offset:4352
	ds_read_b128 v[40:43], v8 offset:64
	ds_read_b128 v[44:47], v8 offset:4416
	ds_read_b128 v[48:51], v8 offset:128
	ds_read_b128 v[52:55], v8 offset:4480
	ds_read_b128 v[56:59], v8 offset:192
	ds_read_b128 v[60:63], v8 offset:4544
	global_load_dwordx4 v[216:219], v1, s[0:1]
	global_load_dwordx4 v[220:223], v1, s[0:1] offset:1024
	s_waitcnt vmcnt(23)
	v_mul_f32_e32 v16, v184, v16
	v_mul_f32_e32 v17, v184, v17
	v_mul_f32_e32 v18, v184, v18
	v_mul_f32_e32 v19, v184, v19
	global_load_dwordx4 v[224:227], v1, s[0:1] offset:2048
	v_mul_f32_e32 v20, v184, v20
	v_mul_f32_e32 v21, v184, v21
	v_mul_f32_e32 v22, v184, v22
	v_mul_f32_e32 v23, v184, v23
	global_load_dwordx4 v[228:231], v1, s[0:1] offset:3072
	s_waitcnt lgkmcnt(6)
	v_mfma_f32_16x16x32_bf16 v[24:27], v[72:75], v[32:35], 0
	v_mfma_f32_16x16x32_bf16 v[28:31], v[72:75], v[36:39], 0
	global_load_dwordx4 v[232:235], v2, s[2:3]
	s_waitcnt lgkmcnt(4)
	v_mfma_f32_16x16x32_bf16 v[24:27], v[76:79], v[40:43], v[24:27]
	v_mfma_f32_16x16x32_bf16 v[28:31], v[76:79], v[44:47], v[28:31]
	global_load_dwordx4 v[236:239], v2, s[2:3] offset:1024
	s_waitcnt lgkmcnt(2)
	v_mfma_f32_16x16x32_bf16 v[24:27], v[80:83], v[48:51], v[24:27]
	v_mfma_f32_16x16x32_bf16 v[28:31], v[80:83], v[52:55], v[28:31]
	global_load_dwordx4 v[240:243], v1, s[4:5]
	s_waitcnt lgkmcnt(0)
	v_mfma_f32_16x16x32_bf16 v[24:27], v[84:87], v[56:59], v[24:27]
	v_mfma_f32_16x16x32_bf16 v[28:31], v[84:87], v[60:63], v[28:31]
	global_load_dwordx4 v[244:247], v1, s[4:5] offset:1024
	global_load_dword v187, v3, s[6:7]
	v_add_u32_e32 v1, 0x4000, v1
	v_add_u32_e32 v2, 0x2000, v2
	v_add_u32_e32 v3, 4, v3
	s_waitcnt lgkmcnt(0)
	s_barrier
	ds_read_b128 v[32:35], v9 offset:17408
	ds_read_b128 v[36:39], v9 offset:19712
	ds_read_b128 v[40:43], v9 offset:17472
	ds_read_b128 v[44:47], v9 offset:19776
	s_waitcnt lgkmcnt(2)
	v_mfma_f32_16x16x32_bf16 v[16:19], v[96:99], v[32:35], v[16:19]
	v_mfma_f32_16x16x32_bf16 v[20:23], v[96:99], v[36:39], v[20:23]
	v_mfma_f32_16x16x32_bf16 v[24:27], v[88:91], v[32:35], v[24:27]
	v_mfma_f32_16x16x32_bf16 v[28:31], v[88:91], v[36:39], v[28:31]
	s_waitcnt lgkmcnt(0)
	v_mfma_f32_16x16x32_bf16 v[16:19], v[100:103], v[40:43], v[16:19]
	v_mfma_f32_16x16x32_bf16 v[20:23], v[100:103], v[44:47], v[20:23]
	v_mfma_f32_16x16x32_bf16 v[24:27], v[92:95], v[40:43], v[24:27]
	v_mfma_f32_16x16x32_bf16 v[28:31], v[92:95], v[44:47], v[28:31]
	s_nop 5
	v_cvt_pk_bf16_f32 v64, v16, v17
	v_cvt_pk_bf16_f32 v65, v18, v19
	v_cvt_pk_bf16_f32 v66, v20, v21
	v_cvt_pk_bf16_f32 v67, v22, v23
	ds_write_b64 v11, v[64:65] offset:8704
	ds_write_b64 v11, v[66:67] offset:13056
	v_cvt_pk_bf16_f32 v68, v24, v25
	v_cvt_pk_bf16_f32 v69, v26, v27
	v_cvt_pk_bf16_f32 v70, v28, v29
	v_cvt_pk_bf16_f32 v71, v30, v31
	ds_write_b16 v13, v68 offset:0
	ds_write_b16_d16_hi v13, v68 offset:80
	ds_write_b16 v13, v69 offset:160
	ds_write_b16_d16_hi v13, v69 offset:240
	ds_write_b16 v13, v70 offset:32
	ds_write_b16_d16_hi v13, v70 offset:112
	ds_write_b16 v13, v71 offset:192
	ds_write_b16_d16_hi v13, v71 offset:272
	ds_read_b128 v[176:179], v172
	s_waitcnt lgkmcnt(0)
	s_barrier
	global_store_dwordx4 v12, v[176:179], s[8:9]
	v_add_u32_e32 v12, 0x20000, v12
	s_waitcnt vmcnt(26)
	ds_read_b128 v[32:35], v8 offset:8704
	ds_read_b128 v[36:39], v8 offset:13056
	ds_read_b128 v[40:43], v8 offset:8768
	ds_read_b128 v[44:47], v8 offset:13120
	ds_read_b128 v[48:51], v8 offset:8832
	ds_read_b128 v[52:55], v8 offset:13184
	ds_read_b128 v[56:59], v8 offset:8896
	ds_read_b128 v[60:63], v8 offset:13248
	global_load_dwordx4 v[72:75], v1, s[0:1]
	global_load_dwordx4 v[76:79], v1, s[0:1] offset:1024
	s_waitcnt vmcnt(23)
	v_mul_f32_e32 v16, v185, v16
	v_mul_f32_e32 v17, v185, v17
	v_mul_f32_e32 v18, v185, v18
	v_mul_f32_e32 v19, v185, v19
	global_load_dwordx4 v[80:83], v1, s[0:1] offset:2048
	v_mul_f32_e32 v20, v185, v20
	v_mul_f32_e32 v21, v185, v21
	v_mul_f32_e32 v22, v185, v22
	v_mul_f32_e32 v23, v185, v23
	global_load_dwordx4 v[84:87], v1, s[0:1] offset:3072
	s_waitcnt lgkmcnt(6)
	v_mfma_f32_16x16x32_bf16 v[24:27], v[104:107], v[32:35], 0
	v_mfma_f32_16x16x32_bf16 v[28:31], v[104:107], v[36:39], 0
	global_load_dwordx4 v[88:91], v2, s[2:3]
	s_waitcnt lgkmcnt(4)
	v_mfma_f32_16x16x32_bf16 v[24:27], v[108:111], v[40:43], v[24:27]
	v_mfma_f32_16x16x32_bf16 v[28:31], v[108:111], v[44:47], v[28:31]
	global_load_dwordx4 v[92:95], v2, s[2:3] offset:1024
	s_waitcnt lgkmcnt(2)
	v_mfma_f32_16x16x32_bf16 v[24:27], v[112:115], v[48:51], v[24:27]
	v_mfma_f32_16x16x32_bf16 v[28:31], v[112:115], v[52:55], v[28:31]
	global_load_dwordx4 v[96:99], v1, s[4:5]
	s_waitcnt lgkmcnt(0)
	v_mfma_f32_16x16x32_bf16 v[24:27], v[116:119], v[56:59], v[24:27]
	v_mfma_f32_16x16x32_bf16 v[28:31], v[116:119], v[60:63], v[28:31]
	global_load_dwordx4 v[100:103], v1, s[4:5] offset:1024
	global_load_dword v184, v3, s[6:7]
	v_add_u32_e32 v1, 0x4000, v1
	v_add_u32_e32 v2, 0x2000, v2
	v_add_u32_e32 v3, 4, v3
	s_waitcnt lgkmcnt(0)
	s_barrier
	ds_read_b128 v[32:35], v9 offset:17408
	ds_read_b128 v[36:39], v9 offset:19712
	ds_read_b128 v[40:43], v9 offset:17472
	ds_read_b128 v[44:47], v9 offset:19776
	s_waitcnt lgkmcnt(2)
	v_mfma_f32_16x16x32_bf16 v[16:19], v[128:131], v[32:35], v[16:19]
	v_mfma_f32_16x16x32_bf16 v[20:23], v[128:131], v[36:39], v[20:23]
	v_mfma_f32_16x16x32_bf16 v[24:27], v[120:123], v[32:35], v[24:27]
	v_mfma_f32_16x16x32_bf16 v[28:31], v[120:123], v[36:39], v[28:31]
	s_waitcnt lgkmcnt(0)
	v_mfma_f32_16x16x32_bf16 v[16:19], v[132:135], v[40:43], v[16:19]
	v_mfma_f32_16x16x32_bf16 v[20:23], v[132:135], v[44:47], v[20:23]
	v_mfma_f32_16x16x32_bf16 v[24:27], v[124:127], v[40:43], v[24:27]
	v_mfma_f32_16x16x32_bf16 v[28:31], v[124:127], v[44:47], v[28:31]
	s_nop 5
	v_cvt_pk_bf16_f32 v64, v16, v17
	v_cvt_pk_bf16_f32 v65, v18, v19
	v_cvt_pk_bf16_f32 v66, v20, v21
	v_cvt_pk_bf16_f32 v67, v22, v23
	ds_write_b64 v11, v[64:65] offset:0
	ds_write_b64 v11, v[66:67] offset:4352
	v_cvt_pk_bf16_f32 v68, v24, v25
	v_cvt_pk_bf16_f32 v69, v26, v27
	v_cvt_pk_bf16_f32 v70, v28, v29
	v_cvt_pk_bf16_f32 v71, v30, v31
	ds_write_b16 v13, v68 offset:0
	ds_write_b16_d16_hi v13, v68 offset:80
	ds_write_b16 v13, v69 offset:160
	ds_write_b16_d16_hi v13, v69 offset:240
	ds_write_b16 v13, v70 offset:32
	ds_write_b16_d16_hi v13, v70 offset:112
	ds_write_b16 v13, v71 offset:192
	ds_write_b16_d16_hi v13, v71 offset:272
	ds_read_b128 v[176:179], v172
	s_waitcnt lgkmcnt(0)
	s_barrier
	global_store_dwordx4 v12, v[176:179], s[8:9]
	v_add_u32_e32 v12, 0x20000, v12
	s_waitcnt vmcnt(26)
	ds_read_b128 v[32:35], v8 offset:0
	ds_read_b128 v[36:39], v8 offset:4352
	ds_read_b128 v[40:43], v8 offset:64
	ds_read_b128 v[44:47], v8 offset:4416
	ds_read_b128 v[48:51], v8 offset:128
	ds_read_b128 v[52:55], v8 offset:4480
	ds_read_b128 v[56:59], v8 offset:192
	ds_read_b128 v[60:63], v8 offset:4544
	global_load_dwordx4 v[104:107], v1, s[0:1]
	global_load_dwordx4 v[108:111], v1, s[0:1] offset:1024
	s_waitcnt vmcnt(23)
	v_mul_f32_e32 v16, v186, v16
	v_mul_f32_e32 v17, v186, v17
	v_mul_f32_e32 v18, v186, v18
	v_mul_f32_e32 v19, v186, v19
	global_load_dwordx4 v[112:115], v1, s[0:1] offset:2048
	v_mul_f32_e32 v20, v186, v20
	v_mul_f32_e32 v21, v186, v21
	v_mul_f32_e32 v22, v186, v22
	v_mul_f32_e32 v23, v186, v23
	global_load_dwordx4 v[116:119], v1, s[0:1] offset:3072
	s_waitcnt lgkmcnt(6)
	v_mfma_f32_16x16x32_bf16 v[24:27], v[136:139], v[32:35], 0
	v_mfma_f32_16x16x32_bf16 v[28:31], v[136:139], v[36:39], 0
	global_load_dwordx4 v[120:123], v2, s[2:3]
	s_waitcnt lgkmcnt(4)
	v_mfma_f32_16x16x32_bf16 v[24:27], v[140:143], v[40:43], v[24:27]
	v_mfma_f32_16x16x32_bf16 v[28:31], v[140:143], v[44:47], v[28:31]
	global_load_dwordx4 v[124:127], v2, s[2:3] offset:1024
	s_waitcnt lgkmcnt(2)
	v_mfma_f32_16x16x32_bf16 v[24:27], v[144:147], v[48:51], v[24:27]
	v_mfma_f32_16x16x32_bf16 v[28:31], v[144:147], v[52:55], v[28:31]
	global_load_dwordx4 v[128:131], v1, s[4:5]
	s_waitcnt lgkmcnt(0)
	v_mfma_f32_16x16x32_bf16 v[24:27], v[148:151], v[56:59], v[24:27]
	v_mfma_f32_16x16x32_bf16 v[28:31], v[148:151], v[60:63], v[28:31]
	global_load_dwordx4 v[132:135], v1, s[4:5] offset:1024
	global_load_dword v185, v3, s[6:7]
	v_add_u32_e32 v1, 0x4000, v1
	v_add_u32_e32 v2, 0x2000, v2
	v_add_u32_e32 v3, 4, v3
	s_waitcnt lgkmcnt(0)
	s_barrier
	ds_read_b128 v[32:35], v9 offset:17408
	ds_read_b128 v[36:39], v9 offset:19712
	ds_read_b128 v[40:43], v9 offset:17472
	ds_read_b128 v[44:47], v9 offset:19776
	s_waitcnt lgkmcnt(2)
	v_mfma_f32_16x16x32_bf16 v[16:19], v[196:199], v[32:35], v[16:19]
	v_mfma_f32_16x16x32_bf16 v[20:23], v[196:199], v[36:39], v[20:23]
	v_mfma_f32_16x16x32_bf16 v[24:27], v[188:191], v[32:35], v[24:27]
	v_mfma_f32_16x16x32_bf16 v[28:31], v[188:191], v[36:39], v[28:31]
	s_waitcnt lgkmcnt(0)
	v_mfma_f32_16x16x32_bf16 v[16:19], v[200:203], v[40:43], v[16:19]
	v_mfma_f32_16x16x32_bf16 v[20:23], v[200:203], v[44:47], v[20:23]
	v_mfma_f32_16x16x32_bf16 v[24:27], v[192:195], v[40:43], v[24:27]
	v_mfma_f32_16x16x32_bf16 v[28:31], v[192:195], v[44:47], v[28:31]
	s_nop 5
	v_cvt_pk_bf16_f32 v64, v16, v17
	v_cvt_pk_bf16_f32 v65, v18, v19
	v_cvt_pk_bf16_f32 v66, v20, v21
	v_cvt_pk_bf16_f32 v67, v22, v23
	ds_write_b64 v11, v[64:65] offset:8704
	ds_write_b64 v11, v[66:67] offset:13056
	v_cvt_pk_bf16_f32 v68, v24, v25
	v_cvt_pk_bf16_f32 v69, v26, v27
	v_cvt_pk_bf16_f32 v70, v28, v29
	v_cvt_pk_bf16_f32 v71, v30, v31
	ds_write_b16 v13, v68 offset:0
	ds_write_b16_d16_hi v13, v68 offset:80
	ds_write_b16 v13, v69 offset:160
	ds_write_b16_d16_hi v13, v69 offset:240
	ds_write_b16 v13, v70 offset:32
	ds_write_b16_d16_hi v13, v70 offset:112
	ds_write_b16 v13, v71 offset:192
	ds_write_b16_d16_hi v13, v71 offset:272
	ds_read_b128 v[176:179], v172
	s_waitcnt lgkmcnt(0)
	s_barrier
	global_store_dwordx4 v12, v[176:179], s[8:9]
	v_add_u32_e32 v12, 0x20000, v12
	s_waitcnt vmcnt(26)
	ds_read_b128 v[32:35], v8 offset:8704
	ds_read_b128 v[36:39], v8 offset:13056
	ds_read_b128 v[40:43], v8 offset:8768
	ds_read_b128 v[44:47], v8 offset:13120
	ds_read_b128 v[48:51], v8 offset:8832
	ds_read_b128 v[52:55], v8 offset:13184
	ds_read_b128 v[56:59], v8 offset:8896
	ds_read_b128 v[60:63], v8 offset:13248
	global_load_dwordx4 v[136:139], v1, s[0:1]
	global_load_dwordx4 v[140:143], v1, s[0:1] offset:1024
	s_waitcnt vmcnt(23)
	v_mul_f32_e32 v16, v187, v16
	v_mul_f32_e32 v17, v187, v17
	v_mul_f32_e32 v18, v187, v18
	v_mul_f32_e32 v19, v187, v19
	global_load_dwordx4 v[144:147], v1, s[0:1] offset:2048
	v_mul_f32_e32 v20, v187, v20
	v_mul_f32_e32 v21, v187, v21
	v_mul_f32_e32 v22, v187, v22
	v_mul_f32_e32 v23, v187, v23
	global_load_dwordx4 v[148:151], v1, s[0:1] offset:3072
	s_waitcnt lgkmcnt(6)
	v_mfma_f32_16x16x32_bf16 v[24:27], v[216:219], v[32:35], 0
	v_mfma_f32_16x16x32_bf16 v[28:31], v[216:219], v[36:39], 0
	global_load_dwordx4 v[188:191], v2, s[2:3]
	s_waitcnt lgkmcnt(4)
	v_mfma_f32_16x16x32_bf16 v[24:27], v[220:223], v[40:43], v[24:27]
	v_mfma_f32_16x16x32_bf16 v[28:31], v[220:223], v[44:47], v[28:31]
	global_load_dwordx4 v[192:195], v2, s[2:3] offset:1024
	s_waitcnt lgkmcnt(2)
	v_mfma_f32_16x16x32_bf16 v[24:27], v[224:227], v[48:51], v[24:27]
	v_mfma_f32_16x16x32_bf16 v[28:31], v[224:227], v[52:55], v[28:31]
	global_load_dwordx4 v[196:199], v1, s[4:5]
	s_waitcnt lgkmcnt(0)
	v_mfma_f32_16x16x32_bf16 v[24:27], v[228:231], v[56:59], v[24:27]
	v_mfma_f32_16x16x32_bf16 v[28:31], v[228:231], v[60:63], v[28:31]
	global_load_dwordx4 v[200:203], v1, s[4:5] offset:1024
	global_load_dword v186, v3, s[6:7]
	v_add_u32_e32 v1, 0x4000, v1
	v_add_u32_e32 v2, 0x2000, v2
	v_add_u32_e32 v3, 4, v3
	s_waitcnt lgkmcnt(0)
	s_barrier
	ds_read_b128 v[32:35], v9 offset:17408
	ds_read_b128 v[36:39], v9 offset:19712
	ds_read_b128 v[40:43], v9 offset:17472
	ds_read_b128 v[44:47], v9 offset:19776
	s_waitcnt lgkmcnt(2)
	v_mfma_f32_16x16x32_bf16 v[16:19], v[240:243], v[32:35], v[16:19]
	v_mfma_f32_16x16x32_bf16 v[20:23], v[240:243], v[36:39], v[20:23]
	v_mfma_f32_16x16x32_bf16 v[24:27], v[232:235], v[32:35], v[24:27]
	v_mfma_f32_16x16x32_bf16 v[28:31], v[232:235], v[36:39], v[28:31]
	s_waitcnt lgkmcnt(0)
	v_mfma_f32_16x16x32_bf16 v[16:19], v[244:247], v[40:43], v[16:19]
	v_mfma_f32_16x16x32_bf16 v[20:23], v[244:247], v[44:47], v[20:23]
	v_mfma_f32_16x16x32_bf16 v[24:27], v[236:239], v[40:43], v[24:27]
	v_mfma_f32_16x16x32_bf16 v[28:31], v[236:239], v[44:47], v[28:31]
	s_nop 5
	v_cvt_pk_bf16_f32 v64, v16, v17
	v_cvt_pk_bf16_f32 v65, v18, v19
	v_cvt_pk_bf16_f32 v66, v20, v21
	v_cvt_pk_bf16_f32 v67, v22, v23
	ds_write_b64 v11, v[64:65] offset:0
	ds_write_b64 v11, v[66:67] offset:4352
	v_cvt_pk_bf16_f32 v68, v24, v25
	v_cvt_pk_bf16_f32 v69, v26, v27
	v_cvt_pk_bf16_f32 v70, v28, v29
	v_cvt_pk_bf16_f32 v71, v30, v31
	ds_write_b16 v13, v68 offset:0
	ds_write_b16_d16_hi v13, v68 offset:80
	ds_write_b16 v13, v69 offset:160
	ds_write_b16_d16_hi v13, v69 offset:240
	ds_write_b16 v13, v70 offset:32
	ds_write_b16_d16_hi v13, v70 offset:112
	ds_write_b16 v13, v71 offset:192
	ds_write_b16_d16_hi v13, v71 offset:272
	ds_read_b128 v[176:179], v172
	s_waitcnt lgkmcnt(0)
	s_barrier
	global_store_dwordx4 v12, v[176:179], s[8:9]
	v_add_u32_e32 v12, 0x20000, v12
	s_sub_u32 s10, s10, 1
	s_cmp_lg_u32 s10, 0
	s_cbranch_scc1 .Lscan_O_loop
